# branch and outproj hand-written GEMM streams shifted by 4 bytes (code placement phase)
# baseline (speedup 1.0000x reference)
.LBB0_207:
	s_andn2_b64 vcc, exec, s[2:3]
	s_cbranch_vccnz .LBB0_313
	s_waitcnt vmcnt(0) lgkmcnt(0)
	v_readlane_b32 s2, v253, 0
	v_readlane_b32 s3, v254, 4
	v_readlane_b32 s30, v252, 0
	v_readlane_b32 s31, v252, 1
	v_readlane_b32 s24, v252, 2
	v_readlane_b32 s25, v252, 3
	v_readlane_b32 s82, v252, 8
	v_readlane_b32 s80, v254, 52
	v_readlane_b32 s81, v254, 53
	s_mov_b32 s18, s10
	s_mov_b32 s19, s11
	s_and_b32 s77, s2, 7
	s_lshl_b32 s77, s77, 2
	s_lshr_b32 s78, s2, 3
	s_lshr_b32 s79, s3, 3
	s_cmp_gt_u32 s78, 31
	s_cbranch_scc1 .LBB0_312
	v_and_b32_e32 v170, 15, v1
	v_bfe_u32 v171, v1, 4, 2
	v_bfe_u32 v172, v1, 6, 1
	v_lshrrev_b32_e32 v173, 7, v1
	v_and_b32_e32 v162, 7, v170
	v_xor_b32_e32 v162, v162, v171
	v_lshlrev_b32_e32 v162, 4, v162
	v_lshlrev_b32_e32 v200, 13, v173
	v_lshl_add_u32 v200, v170, 7, v200
	v_add_u32_e32 v200, v200, v162
	v_xor_b32_e32 v201, 64, v200
	v_lshlrev_b32_e32 v202, 13, v172
	v_lshl_add_u32 v202, v170, 7, v202
	v_add_u32_e32 v202, v202, v162
	v_add_u32_e32 v202, 0x8000, v202
	v_xor_b32_e32 v203, 64, v202
	v_lshl_add_u32 v162, v173, 6, v170
	v_lshlrev_b32_e32 v172, 6, v172
	v_lshl_add_u32 v172, v171, 2, v172
	v_lshlrev_b32_e32 v190, 2, v172
	v_lshlrev_b32_e32 v206, 11, v162
	v_lshl_add_u32 v206, v172, 1, v206
	v_add_u32_e32 v207, 0x8000, v206
	v_add_u32_e32 v208, 0x10000, v206
	v_add_u32_e32 v209, 0x18000, v206
	v_lshlrev_b32_e32 v210, 12, v162
	v_add_u32_e32 v210, v210, v190
	v_add_u32_e32 v211, 0x10000, v210
	v_add_u32_e32 v168, 0x20000, v210
	v_add_u32_e32 v169, 0x30000, v210
	v_lshrrev_b32_e32 v170, 3, v1
	v_and_b32_e32 v171, 7, v1
	v_and_b32_e32 v173, 7, v170
	v_xor_b32_e32 v171, v171, v173
	v_lshlrev_b32_e32 v171, 4, v171
	v_mul_u32_u24_e32 v196, 0x800, v170
	v_add_u32_e32 v196, v196, v171
	v_add_u32_e32 v197, 0x20000, v196
	v_add_u32_e32 v198, 0x40000, v196
	v_add_u32_e32 v199, 0x60000, v196
	v_lshrrev_b32_e32 v170, 6, v1
	v_lshlrev_b32_e32 v170, 10, v170
	s_nop 0
	v_readfirstlane_b32 s76, v170
	s_nop 0

.Lop_exit:
	v_mov_b32_e32 v163, 0
	v_mov_b32_e32 v164, 0x358637bd
	v_mov_b32_e32 v165, 1
	v_mov_b32_e32 v168, 0x2bf
	v_mov_b32_e32 v169, 0
	v_mov_b32_e32 v170, 0x340
	v_mov_b32_e32 v171, 0
	v_mov_b32_e32 v172, 0x33f
	v_mov_b32_e32 v173, 0
	v_mov_b32_e32 v202, 0xc00
	v_mov_b32_e32 v203, 0x7ffffc00
	v_mov_b32_e32 v204, 0xffffff00
	v_mov_b32_e32 v205, 0x400
	v_mov_b32_e32 v206, 0x100
	v_mov_b32_e32 v207, 0x3ff
	v_mov_b32_e32 v208, 0xff
	v_mov_b32_e32 v209, 0xcf
	v_mov_b32_e32 v210, 0xdf
	v_mov_b32_e32 v211, 0xef
	v_mbcnt_lo_u32_b32 v194, -1, 0
	v_mbcnt_hi_u32_b32 v194, -1, v194
	v_and_b32_e32 v195, 64, v194
	v_add_u32_e32 v195, 64, v195
	v_xor_b32_e32 v196, 32, v194
	v_xor_b32_e32 v197, 16, v194
	v_xor_b32_e32 v198, 8, v194
	v_xor_b32_e32 v199, 4, v194
	v_xor_b32_e32 v200, 2, v194
	v_xor_b32_e32 v201, 1, v194
	s_branch .LBB0_312
	s_nop 0

.LBB0_212:
	s_and_b64 vcc, exec, s[2:3]
	s_cbranch_vccz .LBB0_314
	v_readlane_b32 s76, v254, 6
	v_readlane_b32 s84, v254, 8
	v_readlane_b32 s90, v252, 4
	s_cmp_gt_i32 s92, 1
	s_mov_b32 s86, s76
	v_readlane_b32 s85, v254, 9
	v_readlane_b32 s91, v252, 5
	v_readlane_b32 s77, v254, 7
	s_cbranch_scc0 .LBB0_230
	s_cmp_gt_i32 s92, 2
	s_mov_b64 s[2:3], -1
	s_mov_b32 s24, 0x34000
	s_mov_b32 s25, 0x68000
	s_mov_b32 s30, 0x9c000
	s_cbranch_scc0 .LBB0_310
	s_waitcnt vmcnt(0) lgkmcnt(0)
	v_readlane_b32 s2, v253, 0
	v_readlane_b32 s3, v254, 4
	v_readlane_b32 s80, v254, 50
	v_readlane_b32 s81, v254, 51
	s_and_b32 s77, s2, 7
	s_lshl_b32 s77, s77, 2
	s_lshr_b32 s78, s2, 3
	s_lshr_b32 s79, s3, 3
	s_cmp_gt_u32 s78, 31
	s_cbranch_scc1 .LBB0_309
	v_and_b32_e32 v170, 15, v1
	v_bfe_u32 v171, v1, 4, 2
	v_bfe_u32 v172, v1, 6, 1
	v_lshrrev_b32_e32 v173, 7, v1
	v_and_b32_e32 v162, 7, v170
	v_xor_b32_e32 v162, v162, v171
	v_lshlrev_b32_e32 v162, 4, v162
	v_lshlrev_b32_e32 v200, 13, v173
	v_lshl_add_u32 v200, v170, 7, v200
	v_add_u32_e32 v200, v200, v162
	v_xor_b32_e32 v201, 64, v200
	v_lshlrev_b32_e32 v202, 13, v172
	v_lshl_add_u32 v202, v170, 7, v202
	v_add_u32_e32 v202, v202, v162
	v_add_u32_e32 v202, 0x8000, v202
	v_xor_b32_e32 v203, 64, v202
	v_lshl_add_u32 v162, v173, 6, v170
	v_lshlrev_b32_e32 v172, 7, v172
	v_lshl_add_u32 v172, v171, 3, v172
	v_mul_u32_u24_e32 v206, 0x3400, v162
	v_add_u32_e32 v206, v206, v172
	v_add_u32_e32 v207, 0x34000, v206
	v_add_u32_e32 v208, 0x68000, v206
	v_add_u32_e32 v209, 0x9c000, v206
	v_lshl_add_u32 v210, v162, 11, v172
	v_add_u32_e32 v211, 0x8000, v210
	v_add_u32_e32 v168, 0x10000, v210
	v_add_u32_e32 v169, 0x18000, v210
	v_lshrrev_b32_e32 v170, 3, v1
	v_and_b32_e32 v171, 7, v1
	v_and_b32_e32 v173, 7, v170
	v_xor_b32_e32 v171, v171, v173
	v_lshlrev_b32_e32 v171, 4, v171
	v_mul_u32_u24_e32 v196, 0xc00, v170
	v_add_u32_e32 v196, v196, v171
	v_add_u32_e32 v197, 0x30000, v196
	v_add_u32_e32 v198, 0x60000, v196
	v_add_u32_e32 v199, 0x90000, v196
	v_lshrrev_b32_e32 v170, 6, v1
	v_lshlrev_b32_e32 v170, 10, v170
	s_nop 0
	v_readfirstlane_b32 s76, v170
	s_nop 0

.Lbr_exit:
	s_nop 0
	v_mov_b32_e32 v163, 0
	v_mov_b32_e32 v164, 0x358637bd
	v_mov_b32_e32 v165, 1
	v_mov_b32_e32 v168, 0x2bf
	v_mov_b32_e32 v169, 0
	v_mov_b32_e32 v170, 0x340
	v_mov_b32_e32 v171, 0
	v_mov_b32_e32 v172, 0x33f
	v_mov_b32_e32 v173, 0
	v_mov_b32_e32 v202, 0xc00
	v_mov_b32_e32 v203, 0x7ffffc00
	v_mov_b32_e32 v204, 0xffffff00
	v_mov_b32_e32 v205, 0x400
	v_mov_b32_e32 v206, 0x100
	v_mov_b32_e32 v207, 0x3ff
	v_mov_b32_e32 v208, 0xff
	v_mov_b32_e32 v209, 0xcf
	v_mov_b32_e32 v210, 0xdf
	v_mov_b32_e32 v211, 0xef
	v_mbcnt_lo_u32_b32 v194, -1, 0
	v_mbcnt_hi_u32_b32 v194, -1, v194
	v_and_b32_e32 v195, 64, v194
	v_add_u32_e32 v195, 64, v195
	v_xor_b32_e32 v196, 32, v194
	v_xor_b32_e32 v197, 16, v194
	v_xor_b32_e32 v198, 8, v194
	v_xor_b32_e32 v199, 4, v194
	v_xor_b32_e32 v200, 2, v194
	v_xor_b32_e32 v201, 1, v194
	s_branch .LBB0_309
